# v28_vhoist
# speedup vs baseline: 1.0399x; 1.0044x over previous
; __device__ __forceinline__ f32x4 mfma16(bf16x8 a, bf16x8 b, f32x4 c) { return __builtin_amdgcn_mfma_f32_16x16x32_bf16(a, b, c, 0, 0, 0); }
; __device__ __forceinline__ void attn_item(const bf16_t* __restrict__ Q, const bf16_t* __restrict__ Kp, const bf16_t* __restrict__ VT,
;                                           bf16_t* __restrict__ O, int ldo, int nvalid, const float* __restrict__ qn, const float* __restrict__ kn, bf16_t* sm) {
;     ...
;     if (active) {
;       f32x4 s[2][4];
; #pragma unroll
;       for (int g = 0; g < 2; ++g)
; #pragma unroll
;         for (int kt = 0; kt < 4; ++kt) s[g][kt] = f32x4{0.f, 0.f, 0.f, 0.f};
;       {
;         bf16x8 kf[2][4];
; #pragma unroll
;         for (int ks = 0; ks < 4; ++ks) kf[0][ks] = *(const bf16x8*)(sK + (l15) * 136 + ks * 32 + quad * 8);
; #pragma unroll
;         for (int kt = 0; kt < 4; ++kt) {
;           if (kt + 1 < 4) {
; #pragma unroll
;             for (int ks = 0; ks < 4; ++ks) kf[(kt + 1) & 1][ks] = *(const bf16x8*)(sK + ((kt + 1) * 16 + l15) * 136 + ks * 32 + quad * 8);
;           }
;           SCHED();
; #pragma unroll
;           for (int ks = 0; ks < 4; ++ks) {
;             s[0][kt] = mfma16(kf[kt & 1][ks], qf[0][ks], s[0][kt]);
;             s[1][kt] = mfma16(kf[kt & 1][ks], qf[1][ks], s[1][kt]);
;           }
;           SCHED();
;         }
;       }
;       if (k0 + 64 > L) {
; #pragma unroll
;         for (int kt = 0; kt < 4; ++kt)
;           if (k0 + kt * 16 >= L) {
;             s[0][kt] = f32x4{-INFINITY, -INFINITY, -INFINITY, -INFINITY};
;             s[1][kt] = f32x4{-INFINITY, -INFINITY, -INFINITY, -INFINITY};
;           }
;       }
;       bf16x8 pf[2][2];
; #pragma unroll
;       for (int g = 0; g < 2; ++g) {
;         float rs = 0.f;
; #pragma unroll
;         for (int kt = 0; kt < 4; ++kt)
; #pragma unroll
;           for (int j = 0; j < 4; ++j) {
;             float pv = __builtin_amdgcn_exp2f(s[g][kt][j] * cscale - mc);
;             s[g][kt][j] = pv;
;             rs += pv;
;           }
;         l[g] += rs;
; #pragma unroll
;         for (int u = 0; u < 2; ++u) {
;           u32x4 w = {pack2(s[g][2 * u][0], s[g][2 * u][1]), pack2(s[g][2 * u][2], s[g][2 * u][3]),
;                      pack2(s[g][2 * u + 1][0], s[g][2 * u + 1][1]), pack2(s[g][2 * u + 1][2], s[g][2 * u + 1][3])};
;           pf[g][u] = *reinterpret_cast<bf16x8*>(&w);
;         }
;       }
.LBB0_648:
	s_and_saveexec_b64 s[8:9], s[6:7]
	s_cbranch_execz .LBB0_650
	ds_read_b128 v[130:133], v171
	ds_read_b128 v[178:181], v171 offset:64
	ds_read_b128 v[182:185], v171 offset:128
	ds_read_b128 v[186:189], v171 offset:192
	ds_read_b128 v[190:193], v171 offset:4352
	ds_read_b128 v[194:197], v171 offset:4416
	ds_read_b128 v[198:201], v171 offset:4480
	ds_read_b128 v[202:205], v171 offset:4544
	s_waitcnt lgkmcnt(7)
	v_mfma_f32_16x16x32_bf16 v[206:209], v[130:133], v[38:41], 0
	v_mfma_f32_16x16x32_bf16 v[130:133], v[130:133], v[62:65], 0
	s_waitcnt lgkmcnt(6)
	v_mfma_f32_16x16x32_bf16 v[206:209], v[178:181], v[34:37], v[206:209]
	v_mfma_f32_16x16x32_bf16 v[130:133], v[178:181], v[58:61], v[130:133]
	s_waitcnt lgkmcnt(5)
	v_mfma_f32_16x16x32_bf16 v[178:181], v[182:185], v[46:49], v[206:209]
	v_mfma_f32_16x16x32_bf16 v[130:133], v[182:185], v[54:57], v[130:133]
	s_waitcnt lgkmcnt(4)
	v_mfma_f32_16x16x32_bf16 v[178:181], v[186:189], v[42:45], v[178:181]
	v_mfma_f32_16x16x32_bf16 v[182:185], v[186:189], v[50:53], v[130:133]
	s_nop 4
	ds_read_b128 v[130:133], v171 offset:8704
	ds_read_b128 v[186:189], v171 offset:8768
	ds_read_b128 v[206:209], v171 offset:8832
	ds_read_b128 v[210:213], v171 offset:8896
	s_waitcnt lgkmcnt(7)
	v_mfma_f32_16x16x32_bf16 v[214:217], v[190:193], v[38:41], 0
	v_mfma_f32_16x16x32_bf16 v[190:193], v[190:193], v[62:65], 0
	s_waitcnt lgkmcnt(6)
	v_mfma_f32_16x16x32_bf16 v[214:217], v[194:197], v[34:37], v[214:217]
	v_mfma_f32_16x16x32_bf16 v[190:193], v[194:197], v[58:61], v[190:193]
	s_waitcnt lgkmcnt(5)
	v_mfma_f32_16x16x32_bf16 v[194:197], v[198:201], v[46:49], v[214:217]
	v_mfma_f32_16x16x32_bf16 v[190:193], v[198:201], v[54:57], v[190:193]
	s_waitcnt lgkmcnt(4)
	v_mfma_f32_16x16x32_bf16 v[194:197], v[202:205], v[42:45], v[194:197]
	v_mfma_f32_16x16x32_bf16 v[190:193], v[202:205], v[50:53], v[190:193]
	ds_read_b128 v[198:201], v171 offset:13056
	ds_read_b128 v[202:205], v171 offset:13120
	ds_read_b128 v[214:217], v171 offset:13184
	ds_read_b128 v[218:221], v171 offset:13248
	s_waitcnt lgkmcnt(7)
	v_mfma_f32_16x16x32_bf16 v[222:225], v[130:133], v[38:41], 0
	v_mfma_f32_16x16x32_bf16 v[130:133], v[130:133], v[62:65], 0
	s_waitcnt lgkmcnt(6)
	v_mfma_f32_16x16x32_bf16 v[222:225], v[186:189], v[34:37], v[222:225]
	v_mfma_f32_16x16x32_bf16 v[130:133], v[186:189], v[58:61], v[130:133]
	s_waitcnt lgkmcnt(5)
	v_mfma_f32_16x16x32_bf16 v[186:189], v[206:209], v[46:49], v[222:225]
	v_mfma_f32_16x16x32_bf16 v[130:133], v[206:209], v[54:57], v[130:133]
	s_waitcnt lgkmcnt(4)
	v_mfma_f32_16x16x32_bf16 v[186:189], v[210:213], v[42:45], v[186:189]
	v_mfma_f32_16x16x32_bf16 v[206:209], v[210:213], v[50:53], v[130:133]
	s_waitcnt lgkmcnt(3)
	v_mfma_f32_16x16x32_bf16 v[130:133], v[198:201], v[38:41], 0
	v_mfma_f32_16x16x32_bf16 v[198:201], v[198:201], v[62:65], 0
	s_waitcnt lgkmcnt(2)
	v_mfma_f32_16x16x32_bf16 v[130:133], v[202:205], v[34:37], v[130:133]
	v_mfma_f32_16x16x32_bf16 v[198:201], v[202:205], v[58:61], v[198:201]
	s_waitcnt lgkmcnt(1)
	v_mfma_f32_16x16x32_bf16 v[130:133], v[214:217], v[46:49], v[130:133]
	v_mfma_f32_16x16x32_bf16 v[198:201], v[214:217], v[54:57], v[198:201]
	s_waitcnt lgkmcnt(0)
	v_mfma_f32_16x16x32_bf16 v[130:133], v[218:221], v[42:45], v[130:133]
	v_mfma_f32_16x16x32_bf16 v[198:201], v[218:221], v[50:53], v[198:201]
	v_add_u32_e32 v246, 0x8800, v149
	v_add_u32_e32 v247, 0x9000, v149
	v_add_u32_e32 v248, 0x9800, v149
	v_add_u32_e32 v249, 0xa000, v149
	ds_read2_b64 v[230:233], v246 offset1:4
	ds_read2_b64 v[234:237], v247 offset0:32 offset1:36
	ds_read2_b64 v[238:241], v248 offset0:64 offset1:68
	ds_read2_b64 v[242:245], v249 offset0:96 offset1:100
	v_fma_f32 v0, v178, s53, -v170
	v_exp_f32_e32 v202, v0
	v_fma_f32 v0, v179, s53, -v170
	v_exp_f32_e32 v204, v0
	v_fma_f32 v0, v180, s53, -v170
	v_exp_f32_e32 v210, v0
	v_fma_f32 v0, v181, s53, -v170
	v_exp_f32_e32 v212, v0
	v_fma_f32 v0, v194, s53, -v170
	v_exp_f32_e32 v194, v0
	v_fma_f32 v0, v195, s53, -v170
	v_exp_f32_e32 v214, v0
	v_fma_f32 v0, v196, s53, -v170
	v_exp_f32_e32 v196, v0
	v_fma_f32 v0, v197, s53, -v170
	v_exp_f32_e32 v216, v0
	v_fma_f32 v0, v186, s53, -v170
	v_exp_f32_e32 v186, v0
	v_fma_f32 v0, v187, s53, -v170
	v_exp_f32_e32 v218, v0
	v_fma_f32 v0, v188, s53, -v170
	v_exp_f32_e32 v188, v0
	v_fma_f32 v0, v189, s53, -v170
	v_exp_f32_e32 v220, v0
	v_fma_f32 v0, v130, s53, -v170
	v_exp_f32_e32 v222, v0
	v_fma_f32 v0, v131, s53, -v170
	v_exp_f32_e32 v224, v0
	v_fma_f32 v0, v132, s53, -v170
	v_exp_f32_e32 v226, v0
	v_fma_f32 v0, v133, s53, -v170
	v_exp_f32_e32 v228, v0
	v_fma_f32 v0, v182, s53, -v170
	v_exp_f32_e32 v203, v0
	v_fma_f32 v0, v183, s53, -v170
	v_exp_f32_e32 v205, v0
	v_fma_f32 v0, v184, s53, -v170
	v_exp_f32_e32 v211, v0
	v_fma_f32 v0, v185, s53, -v170
	v_exp_f32_e32 v213, v0
	v_fma_f32 v0, v190, s53, -v170
	v_exp_f32_e32 v195, v0
	v_fma_f32 v0, v191, s53, -v170
	v_pk_add_f32 v[182:183], v[202:203], 0 op_sel_hi:[1,0]
	v_exp_f32_e32 v215, v0
	v_fma_f32 v0, v192, s53, -v170
	v_pk_add_f32 v[182:183], v[204:205], v[182:183]
	v_exp_f32_e32 v197, v0
	v_fma_f32 v0, v193, s53, -v170
	v_pk_add_f32 v[182:183], v[210:211], v[182:183]
	v_exp_f32_e32 v217, v0
	v_fma_f32 v0, v206, s53, -v170
; __device__ __forceinline__ f32x4 mfma16(bf16x8 a, bf16x8 b, f32x4 c) { return __builtin_amdgcn_mfma_f32_16x16x32_bf16(a, b, c, 0, 0, 0); }
; #define SCHED() __builtin_amdgcn_sched_barrier(0)
; __device__ __forceinline__ void attn_item(const bf16_t* __restrict__ Q, const bf16_t* __restrict__ Kp, const bf16_t* __restrict__ VT,
;                                           bf16_t* __restrict__ O, int ldo, int nvalid, const float* __restrict__ qn, const float* __restrict__ kn, bf16_t* sm) {
;     ...
;       bf16x8 pf[2][2];
; #pragma unroll
;       for (int g = 0; g < 2; ++g) {
;         float rs = 0.f;
; #pragma unroll
;         for (int kt = 0; kt < 4; ++kt)
; #pragma unroll
;           for (int j = 0; j < 4; ++j) {
;             float pv = __builtin_amdgcn_exp2f(s[g][kt][j] * cscale - mc);
;             s[g][kt][j] = pv;
;             rs += pv;
;           }
;         l[g] += rs;
; #pragma unroll
;         for (int u = 0; u < 2; ++u) {
;           u32x4 w = {pack2(s[g][2 * u][0], s[g][2 * u][1]), pack2(s[g][2 * u][2], s[g][2 * u][3]),
;                      pack2(s[g][2 * u + 1][0], s[g][2 * u + 1][1]), pack2(s[g][2 * u + 1][2], s[g][2 * u + 1][3])};
;           pf[g][u] = *reinterpret_cast<bf16x8*>(&w);
;         }
;       }
; #pragma unroll
;       for (int u = 0; u < 2; ++u) {
;         bf16x8 vf[8];
; #pragma unroll
;         for (int dt = 0; dt < 8; ++dt) {
;           u32x2 v0 = *(const u32x2*)(sV + (dt * 16 + l15) * 72 + (2 * u) * 16 + quad * 4);
;           u32x2 v1 = *(const u32x2*)(sV + (dt * 16 + l15) * 72 + (2 * u + 1) * 16 + quad * 4);
;           u32x4 w = {v0.x, v0.y, v1.x, v1.y};
;           vf[dt] = *reinterpret_cast<bf16x8*>(&w);
;         }
;         SCHED();
; #pragma unroll
;         for (int dt = 0; dt < 8; ++dt) {
;           o[0][dt] = mfma16(vf[dt], pf[0][u], o[0][dt]);
;           o[1][dt] = mfma16(vf[dt], pf[1][u], o[1][dt]);
;         }
;         SCHED();
;       }
	v_pk_add_f32 v[182:183], v[212:213], v[182:183]
	v_exp_f32_e32 v187, v0
	v_fma_f32 v0, v207, s53, -v170
	v_pk_add_f32 v[182:183], v[182:183], v[194:195]
	v_exp_f32_e32 v219, v0
	v_pk_add_f32 v[182:183], v[214:215], v[182:183]
	v_fma_f32 v0, v208, s53, -v170
	v_pk_add_f32 v[182:183], v[196:197], v[182:183]
	v_exp_f32_e32 v189, v0
	v_fma_f32 v0, v209, s53, -v170
	v_pk_add_f32 v[182:183], v[216:217], v[182:183]
	v_exp_f32_e32 v221, v0
	v_fma_f32 v0, v198, s53, -v170
	v_pk_add_f32 v[182:183], v[182:183], v[186:187]
	v_exp_f32_e32 v223, v0
	v_fma_f32 v0, v199, s53, -v170
	v_pk_add_f32 v[182:183], v[218:219], v[182:183]
	v_exp_f32_e32 v225, v0
	v_fma_f32 v0, v200, s53, -v170
	v_exp_f32_e32 v227, v0
	v_fma_f32 v0, v201, s53, -v170
	v_pk_add_f32 v[182:183], v[188:189], v[182:183]
	v_exp_f32_e32 v229, v0
	v_pk_add_f32 v[182:183], v[220:221], v[182:183]
	v_cvt_pk_bf16_f32 v178, v202, v204
	v_cvt_pk_bf16_f32 v179, v210, v212
	v_cvt_pk_bf16_f32 v180, v194, v214
	v_cvt_pk_bf16_f32 v181, v196, v216
	v_cvt_pk_bf16_f32 v130, v186, v218
	s_nop 0
	v_pk_add_f32 v[182:183], v[182:183], v[222:223]
	v_cvt_pk_bf16_f32 v131, v188, v220
	v_cvt_pk_bf16_f32 v132, v222, v224
	v_cvt_pk_bf16_f32 v133, v226, v228
	v_add_u32_e32 v0, 0x8800, v149
	v_pk_add_f32 v[182:183], v[224:225], v[182:183]
	v_add_u32_e32 v222, 0x9000, v149
	v_pk_add_f32 v[182:183], v[226:227], v[182:183]
	v_add_u32_e32 v224, 0xa000, v149
	v_pk_add_f32 v[182:183], v[228:229], v[182:183]
	v_add_u32_e32 v226, 0xb000, v149
	v_pk_add_f32 v[144:145], v[144:145], v[182:183]
	v_cvt_pk_bf16_f32 v182, v203, v205
	v_cvt_pk_bf16_f32 v183, v211, v213
	v_cvt_pk_bf16_f32 v184, v195, v215
	v_cvt_pk_bf16_f32 v185, v197, v217
	v_cvt_pk_bf16_f32 v186, v187, v219
	v_cvt_pk_bf16_f32 v187, v189, v221
	v_cvt_pk_bf16_f32 v188, v223, v225
	v_cvt_pk_bf16_f32 v189, v227, v229
	v_add_u32_e32 v223, 0x9800, v149
	v_add_u32_e32 v225, 0xa800, v149
	v_add_u32_e32 v227, 0xb800, v149
	v_add_u32_e32 v228, 0xc000, v149
	ds_read2_b64 v[206:209], v225 offset0:128 offset1:132
	ds_read2_b64 v[210:213], v226 offset0:160 offset1:164
	ds_read2_b64 v[214:217], v227 offset0:192 offset1:196
	ds_read2_b64 v[218:221], v228 offset0:224 offset1:228
	s_waitcnt lgkmcnt(7)
	v_mfma_f32_16x16x32_bf16 v[94:97], v[230:233], v[178:181], v[94:97]
	v_mfma_f32_16x16x32_bf16 v[30:33], v[230:233], v[182:185], v[30:33]
	s_waitcnt lgkmcnt(6)
	v_mfma_f32_16x16x32_bf16 v[90:93], v[234:237], v[178:181], v[90:93]
	v_mfma_f32_16x16x32_bf16 v[26:29], v[234:237], v[182:185], v[26:29]
	s_waitcnt lgkmcnt(5)
	v_mfma_f32_16x16x32_bf16 v[86:89], v[238:241], v[178:181], v[86:89]
	v_mfma_f32_16x16x32_bf16 v[22:25], v[238:241], v[182:185], v[22:25]
	s_waitcnt lgkmcnt(4)
	v_mfma_f32_16x16x32_bf16 v[82:85], v[242:245], v[178:181], v[82:85]
	v_mfma_f32_16x16x32_bf16 v[18:21], v[242:245], v[182:185], v[18:21]
	s_waitcnt lgkmcnt(3)
	v_mfma_f32_16x16x32_bf16 v[78:81], v[206:209], v[178:181], v[78:81]
	v_mfma_f32_16x16x32_bf16 v[14:17], v[206:209], v[182:185], v[14:17]
	s_waitcnt lgkmcnt(2)
	v_mfma_f32_16x16x32_bf16 v[74:77], v[210:213], v[178:181], v[74:77]
	v_mfma_f32_16x16x32_bf16 v[10:13], v[210:213], v[182:185], v[10:13]
	s_waitcnt lgkmcnt(1)
	v_mfma_f32_16x16x32_bf16 v[70:73], v[214:217], v[178:181], v[70:73]
	v_mfma_f32_16x16x32_bf16 v[6:9], v[214:217], v[182:185], v[6:9]
	s_waitcnt lgkmcnt(0)
	v_mfma_f32_16x16x32_bf16 v[66:69], v[218:221], v[178:181], v[66:69]
	v_mfma_f32_16x16x32_bf16 v[2:5], v[218:221], v[182:185], v[2:5]
	ds_read2_b64 v[178:181], v0 offset0:8 offset1:12
	ds_read2_b64 v[182:185], v222 offset0:40 offset1:44
	ds_read2_b64 v[190:193], v223 offset0:72 offset1:76
	ds_read2_b64 v[194:197], v224 offset0:104 offset1:108
	ds_read2_b64 v[198:201], v225 offset0:136 offset1:140
	ds_read2_b64 v[202:205], v226 offset0:168 offset1:172
	ds_read2_b64 v[206:209], v227 offset0:200 offset1:204
	ds_read2_b64 v[210:213], v228 offset0:232 offset1:236
	s_waitcnt lgkmcnt(7)
	v_mfma_f32_16x16x32_bf16 v[94:97], v[178:181], v[130:133], v[94:97]
	v_mfma_f32_16x16x32_bf16 v[30:33], v[178:181], v[186:189], v[30:33]
	s_waitcnt lgkmcnt(6)
	v_mfma_f32_16x16x32_bf16 v[90:93], v[182:185], v[130:133], v[90:93]
	v_mfma_f32_16x16x32_bf16 v[26:29], v[182:185], v[186:189], v[26:29]
	s_waitcnt lgkmcnt(5)
	v_mfma_f32_16x16x32_bf16 v[86:89], v[190:193], v[130:133], v[86:89]
	v_mfma_f32_16x16x32_bf16 v[22:25], v[190:193], v[186:189], v[22:25]
	s_waitcnt lgkmcnt(4)
	v_mfma_f32_16x16x32_bf16 v[82:85], v[194:197], v[130:133], v[82:85]
	v_mfma_f32_16x16x32_bf16 v[18:21], v[194:197], v[186:189], v[18:21]
	s_waitcnt lgkmcnt(3)
	v_mfma_f32_16x16x32_bf16 v[78:81], v[198:201], v[130:133], v[78:81]
	v_mfma_f32_16x16x32_bf16 v[14:17], v[198:201], v[186:189], v[14:17]
	s_waitcnt lgkmcnt(2)
	v_mfma_f32_16x16x32_bf16 v[74:77], v[202:205], v[130:133], v[74:77]
	v_mfma_f32_16x16x32_bf16 v[10:13], v[202:205], v[186:189], v[10:13]
	s_waitcnt lgkmcnt(1)
	v_mfma_f32_16x16x32_bf16 v[70:73], v[206:209], v[130:133], v[70:73]
	v_mfma_f32_16x16x32_bf16 v[6:9], v[206:209], v[186:189], v[6:9]
	s_waitcnt lgkmcnt(0)
	v_mfma_f32_16x16x32_bf16 v[66:69], v[210:213], v[130:133], v[66:69]
	v_mfma_f32_16x16x32_bf16 v[2:5], v[210:213], v[186:189], v[2:5]

; __device__ __forceinline__ f32x4 mfma16(bf16x8 a, bf16x8 b, f32x4 c) { return __builtin_amdgcn_mfma_f32_16x16x32_bf16(a, b, c, 0, 0, 0); }
; __device__ __forceinline__ void attn_item(const bf16_t* __restrict__ Q, const bf16_t* __restrict__ Kp, const bf16_t* __restrict__ VT,
;                                           bf16_t* __restrict__ O, int ldo, int nvalid, const float* __restrict__ qn, const float* __restrict__ kn, bf16_t* sm) {
;     ...
;     if (active) {
;       f32x4 s[2][4];
; #pragma unroll
;       for (int g = 0; g < 2; ++g)
; #pragma unroll
;         for (int kt = 0; kt < 4; ++kt) s[g][kt] = f32x4{0.f, 0.f, 0.f, 0.f};
;       {
;         bf16x8 kf[2][4];
; #pragma unroll
;         for (int ks = 0; ks < 4; ++ks) kf[0][ks] = *(const bf16x8*)(sK + (l15) * 136 + ks * 32 + quad * 8);
; #pragma unroll
;         for (int kt = 0; kt < 4; ++kt) {
;           if (kt + 1 < 4) {
; #pragma unroll
;             for (int ks = 0; ks < 4; ++ks) kf[(kt + 1) & 1][ks] = *(const bf16x8*)(sK + ((kt + 1) * 16 + l15) * 136 + ks * 32 + quad * 8);
;           }
;           SCHED();
; #pragma unroll
;           for (int ks = 0; ks < 4; ++ks) {
;             s[0][kt] = mfma16(kf[kt & 1][ks], qf[0][ks], s[0][kt]);
;             s[1][kt] = mfma16(kf[kt & 1][ks], qf[1][ks], s[1][kt]);
;           }
;           SCHED();
;         }
;       }
;       if (k0 + 64 > L) {
; #pragma unroll
;         for (int kt = 0; kt < 4; ++kt)
;           if (k0 + kt * 16 >= L) {
;             s[0][kt] = f32x4{-INFINITY, -INFINITY, -INFINITY, -INFINITY};
;             s[1][kt] = f32x4{-INFINITY, -INFINITY, -INFINITY, -INFINITY};
;           }
;       }
;       bf16x8 pf[2][2];
; #pragma unroll
;       for (int g = 0; g < 2; ++g) {
;         float rs = 0.f;
; #pragma unroll
;         for (int kt = 0; kt < 4; ++kt)
; #pragma unroll
;           for (int j = 0; j < 4; ++j) {
;             float pv = __builtin_amdgcn_exp2f(s[g][kt][j] * cscale - mc);
;             s[g][kt][j] = pv;
;             rs += pv;
;           }
;         l[g] += rs;
; #pragma unroll
;         for (int u = 0; u < 2; ++u) {
;           u32x4 w = {pack2(s[g][2 * u][0], s[g][2 * u][1]), pack2(s[g][2 * u][2], s[g][2 * u][3]),
;                      pack2(s[g][2 * u + 1][0], s[g][2 * u + 1][1]), pack2(s[g][2 * u + 1][2], s[g][2 * u + 1][3])};
;           pf[g][u] = *reinterpret_cast<bf16x8*>(&w);
;         }
;       }
.LBB0_652:
	s_and_saveexec_b64 s[8:9], s[6:7]
	s_cbranch_execz .LBB0_645
	ds_read_b128 v[130:133], v171 offset:17408
	ds_read_b128 v[178:181], v171 offset:17472
	ds_read_b128 v[182:185], v171 offset:17536
	ds_read_b128 v[186:189], v171 offset:17600
	ds_read_b128 v[190:193], v171 offset:21760
	ds_read_b128 v[194:197], v171 offset:21824
	ds_read_b128 v[198:201], v171 offset:21888
	ds_read_b128 v[202:205], v171 offset:21952
	s_waitcnt lgkmcnt(7)
	v_mfma_f32_16x16x32_bf16 v[206:209], v[130:133], v[38:41], 0
	v_mfma_f32_16x16x32_bf16 v[130:133], v[130:133], v[62:65], 0
	s_waitcnt lgkmcnt(6)
	v_mfma_f32_16x16x32_bf16 v[206:209], v[178:181], v[34:37], v[206:209]
	v_mfma_f32_16x16x32_bf16 v[130:133], v[178:181], v[58:61], v[130:133]
	s_waitcnt lgkmcnt(5)
	v_mfma_f32_16x16x32_bf16 v[178:181], v[182:185], v[46:49], v[206:209]
	v_mfma_f32_16x16x32_bf16 v[130:133], v[182:185], v[54:57], v[130:133]
	s_waitcnt lgkmcnt(4)
	v_mfma_f32_16x16x32_bf16 v[178:181], v[186:189], v[42:45], v[178:181]
	v_mfma_f32_16x16x32_bf16 v[182:185], v[186:189], v[50:53], v[130:133]
	s_nop 4
	ds_read_b128 v[130:133], v171 offset:26112
	ds_read_b128 v[186:189], v171 offset:26176
	ds_read_b128 v[206:209], v171 offset:26240
	ds_read_b128 v[210:213], v171 offset:26304
	s_waitcnt lgkmcnt(7)
	v_mfma_f32_16x16x32_bf16 v[214:217], v[190:193], v[38:41], 0
	v_mfma_f32_16x16x32_bf16 v[190:193], v[190:193], v[62:65], 0
	s_waitcnt lgkmcnt(6)
	v_mfma_f32_16x16x32_bf16 v[214:217], v[194:197], v[34:37], v[214:217]
	v_mfma_f32_16x16x32_bf16 v[190:193], v[194:197], v[58:61], v[190:193]
	s_waitcnt lgkmcnt(5)
	v_mfma_f32_16x16x32_bf16 v[194:197], v[198:201], v[46:49], v[214:217]
	v_mfma_f32_16x16x32_bf16 v[190:193], v[198:201], v[54:57], v[190:193]
	s_waitcnt lgkmcnt(4)
	v_mfma_f32_16x16x32_bf16 v[194:197], v[202:205], v[42:45], v[194:197]
	v_mfma_f32_16x16x32_bf16 v[190:193], v[202:205], v[50:53], v[190:193]
	ds_read_b128 v[198:201], v171 offset:30464
	ds_read_b128 v[202:205], v171 offset:30528
	ds_read_b128 v[214:217], v171 offset:30592
	ds_read_b128 v[218:221], v171 offset:30656
	s_waitcnt lgkmcnt(7)
	v_mfma_f32_16x16x32_bf16 v[222:225], v[130:133], v[38:41], 0
	v_mfma_f32_16x16x32_bf16 v[130:133], v[130:133], v[62:65], 0
	s_waitcnt lgkmcnt(6)
	v_mfma_f32_16x16x32_bf16 v[222:225], v[186:189], v[34:37], v[222:225]
	v_mfma_f32_16x16x32_bf16 v[130:133], v[186:189], v[58:61], v[130:133]
	s_waitcnt lgkmcnt(5)
	v_mfma_f32_16x16x32_bf16 v[186:189], v[206:209], v[46:49], v[222:225]
	v_mfma_f32_16x16x32_bf16 v[130:133], v[206:209], v[54:57], v[130:133]
	s_waitcnt lgkmcnt(4)
	v_mfma_f32_16x16x32_bf16 v[186:189], v[210:213], v[42:45], v[186:189]
	v_mfma_f32_16x16x32_bf16 v[206:209], v[210:213], v[50:53], v[130:133]
	s_waitcnt lgkmcnt(3)
	v_mfma_f32_16x16x32_bf16 v[130:133], v[198:201], v[38:41], 0
	v_mfma_f32_16x16x32_bf16 v[198:201], v[198:201], v[62:65], 0
	s_waitcnt lgkmcnt(2)
	v_mfma_f32_16x16x32_bf16 v[130:133], v[202:205], v[34:37], v[130:133]
	v_mfma_f32_16x16x32_bf16 v[198:201], v[202:205], v[58:61], v[198:201]
	s_waitcnt lgkmcnt(1)
	v_mfma_f32_16x16x32_bf16 v[130:133], v[214:217], v[46:49], v[130:133]
	v_mfma_f32_16x16x32_bf16 v[198:201], v[214:217], v[54:57], v[198:201]
	s_waitcnt lgkmcnt(0)
	v_mfma_f32_16x16x32_bf16 v[130:133], v[218:221], v[42:45], v[130:133]
	v_mfma_f32_16x16x32_bf16 v[198:201], v[218:221], v[50:53], v[198:201]
	v_add_u32_e32 v247, 0xd800, v149
	v_add_u32_e32 v248, 0xe000, v149
	v_add_u32_e32 v249, 0xe800, v149
	s_nop 0
	ds_read2_b64 v[230:233], v172 offset1:4
	ds_read2_b64 v[234:237], v247 offset0:32 offset1:36
	ds_read2_b64 v[238:241], v248 offset0:64 offset1:68
	ds_read2_b64 v[242:245], v249 offset0:96 offset1:100
	v_fma_f32 v0, v178, s53, -v170
	v_exp_f32_e32 v202, v0
	v_fma_f32 v0, v179, s53, -v170
	v_exp_f32_e32 v204, v0
	v_fma_f32 v0, v180, s53, -v170
	v_exp_f32_e32 v210, v0
	v_fma_f32 v0, v181, s53, -v170
	v_exp_f32_e32 v212, v0
	v_fma_f32 v0, v194, s53, -v170
	v_exp_f32_e32 v194, v0
	v_fma_f32 v0, v195, s53, -v170
	v_exp_f32_e32 v214, v0
	v_fma_f32 v0, v196, s53, -v170
	v_exp_f32_e32 v196, v0
	v_fma_f32 v0, v197, s53, -v170
	v_exp_f32_e32 v216, v0
	v_fma_f32 v0, v186, s53, -v170
	v_exp_f32_e32 v186, v0
	v_fma_f32 v0, v187, s53, -v170
	v_exp_f32_e32 v218, v0
	v_fma_f32 v0, v188, s53, -v170
	v_exp_f32_e32 v188, v0
	v_fma_f32 v0, v189, s53, -v170
	v_exp_f32_e32 v220, v0
	v_fma_f32 v0, v130, s53, -v170
	v_exp_f32_e32 v222, v0
	v_fma_f32 v0, v131, s53, -v170
	v_exp_f32_e32 v224, v0
	v_fma_f32 v0, v132, s53, -v170
	v_exp_f32_e32 v226, v0
	v_fma_f32 v0, v133, s53, -v170
	v_exp_f32_e32 v228, v0
	v_fma_f32 v0, v182, s53, -v170
	v_exp_f32_e32 v203, v0
	v_fma_f32 v0, v183, s53, -v170
	v_exp_f32_e32 v205, v0
	v_fma_f32 v0, v184, s53, -v170
	v_exp_f32_e32 v211, v0
	v_fma_f32 v0, v185, s53, -v170
	v_exp_f32_e32 v213, v0
	v_fma_f32 v0, v190, s53, -v170
	v_exp_f32_e32 v195, v0
	v_fma_f32 v0, v191, s53, -v170
	v_pk_add_f32 v[182:183], v[202:203], 0 op_sel_hi:[1,0]
	v_exp_f32_e32 v215, v0
	v_fma_f32 v0, v192, s53, -v170
	v_pk_add_f32 v[182:183], v[204:205], v[182:183]
	v_exp_f32_e32 v197, v0
	v_fma_f32 v0, v193, s53, -v170
	v_pk_add_f32 v[182:183], v[210:211], v[182:183]
	v_exp_f32_e32 v217, v0
	v_pk_add_f32 v[182:183], v[212:213], v[182:183]
; __device__ __forceinline__ f32x4 mfma16(bf16x8 a, bf16x8 b, f32x4 c) { return __builtin_amdgcn_mfma_f32_16x16x32_bf16(a, b, c, 0, 0, 0); }
; #define SCHED() __builtin_amdgcn_sched_barrier(0)
; __device__ __forceinline__ void attn_item(const bf16_t* __restrict__ Q, const bf16_t* __restrict__ Kp, const bf16_t* __restrict__ VT,
;                                           bf16_t* __restrict__ O, int ldo, int nvalid, const float* __restrict__ qn, const float* __restrict__ kn, bf16_t* sm) {
;     ...
;       bf16x8 pf[2][2];
; #pragma unroll
;       for (int g = 0; g < 2; ++g) {
;         float rs = 0.f;
; #pragma unroll
;         for (int kt = 0; kt < 4; ++kt)
; #pragma unroll
;           for (int j = 0; j < 4; ++j) {
;             float pv = __builtin_amdgcn_exp2f(s[g][kt][j] * cscale - mc);
;             s[g][kt][j] = pv;
;             rs += pv;
;           }
;         l[g] += rs;
; #pragma unroll
;         for (int u = 0; u < 2; ++u) {
;           u32x4 w = {pack2(s[g][2 * u][0], s[g][2 * u][1]), pack2(s[g][2 * u][2], s[g][2 * u][3]),
;                      pack2(s[g][2 * u + 1][0], s[g][2 * u + 1][1]), pack2(s[g][2 * u + 1][2], s[g][2 * u + 1][3])};
;           pf[g][u] = *reinterpret_cast<bf16x8*>(&w);
;         }
;       }
; #pragma unroll
;       for (int u = 0; u < 2; ++u) {
;         bf16x8 vf[8];
; #pragma unroll
;         for (int dt = 0; dt < 8; ++dt) {
;           u32x2 v0 = *(const u32x2*)(sV + (dt * 16 + l15) * 72 + (2 * u) * 16 + quad * 4);
;           u32x2 v1 = *(const u32x2*)(sV + (dt * 16 + l15) * 72 + (2 * u + 1) * 16 + quad * 4);
;           u32x4 w = {v0.x, v0.y, v1.x, v1.y};
;           vf[dt] = *reinterpret_cast<bf16x8*>(&w);
;         }
;         SCHED();
; #pragma unroll
;         for (int dt = 0; dt < 8; ++dt) {
;           o[0][dt] = mfma16(vf[dt], pf[0][u], o[0][dt]);
;           o[1][dt] = mfma16(vf[dt], pf[1][u], o[1][dt]);
;         }
;         SCHED();
;       }
	v_fma_f32 v0, v206, s53, -v170
	v_pk_add_f32 v[182:183], v[182:183], v[194:195]
	v_exp_f32_e32 v187, v0
	v_fma_f32 v0, v207, s53, -v170
	v_pk_add_f32 v[182:183], v[214:215], v[182:183]
	v_exp_f32_e32 v219, v0
	v_fma_f32 v0, v208, s53, -v170
	v_pk_add_f32 v[182:183], v[196:197], v[182:183]
	v_exp_f32_e32 v189, v0
	v_fma_f32 v0, v209, s53, -v170
	v_pk_add_f32 v[182:183], v[216:217], v[182:183]
	v_exp_f32_e32 v221, v0
	v_fma_f32 v0, v198, s53, -v170
	v_exp_f32_e32 v223, v0
	v_fma_f32 v0, v199, s53, -v170
	v_pk_add_f32 v[182:183], v[182:183], v[186:187]
	v_exp_f32_e32 v225, v0
	v_fma_f32 v0, v200, s53, -v170
	v_pk_add_f32 v[182:183], v[218:219], v[182:183]
	v_exp_f32_e32 v227, v0
	v_fma_f32 v0, v201, s53, -v170
	v_pk_add_f32 v[182:183], v[188:189], v[182:183]
	v_exp_f32_e32 v229, v0
	v_pk_add_f32 v[182:183], v[220:221], v[182:183]
	v_cvt_pk_bf16_f32 v178, v202, v204
	v_cvt_pk_bf16_f32 v179, v210, v212
	v_cvt_pk_bf16_f32 v180, v194, v214
	v_cvt_pk_bf16_f32 v181, v196, v216
	v_cvt_pk_bf16_f32 v130, v186, v218
	s_nop 0
	v_pk_add_f32 v[182:183], v[182:183], v[222:223]
	v_cvt_pk_bf16_f32 v131, v188, v220
	v_cvt_pk_bf16_f32 v132, v222, v224
	v_cvt_pk_bf16_f32 v133, v226, v228
	v_add_u32_e32 v0, 0xd800, v149
	v_pk_add_f32 v[182:183], v[224:225], v[182:183]
	v_add_u32_e32 v222, 0xe000, v149
	v_pk_add_f32 v[182:183], v[226:227], v[182:183]
	v_add_u32_e32 v224, 0xf000, v149
	v_pk_add_f32 v[182:183], v[228:229], v[182:183]
	s_nop 0
	v_pk_add_f32 v[144:145], v[144:145], v[182:183]
	v_cvt_pk_bf16_f32 v182, v203, v205
	v_cvt_pk_bf16_f32 v183, v211, v213
	v_cvt_pk_bf16_f32 v184, v195, v215
	v_cvt_pk_bf16_f32 v185, v197, v217
	v_cvt_pk_bf16_f32 v186, v187, v219
	v_cvt_pk_bf16_f32 v187, v189, v221
	v_cvt_pk_bf16_f32 v188, v223, v225
	v_add_u32_e32 v223, 0xe800, v149
	v_add_u32_e32 v225, 0xf800, v149
	v_cvt_pk_bf16_f32 v189, v227, v229
	ds_read2_b64 v[206:209], v224 offset0:128 offset1:132
	ds_read2_b64 v[210:213], v225 offset0:160 offset1:164
	ds_read_b64 v[214:215], v172 offset:13824
	ds_read_b64 v[216:217], v173 offset:32
	ds_read_b64 v[218:219], v172 offset:16128
	ds_read_b64 v[220:221], v174 offset:32
	s_waitcnt lgkmcnt(9)
	v_mfma_f32_16x16x32_bf16 v[94:97], v[230:233], v[178:181], v[94:97]
	v_mfma_f32_16x16x32_bf16 v[30:33], v[230:233], v[182:185], v[30:33]
	s_waitcnt lgkmcnt(8)
	v_mfma_f32_16x16x32_bf16 v[90:93], v[234:237], v[178:181], v[90:93]
	v_mfma_f32_16x16x32_bf16 v[26:29], v[234:237], v[182:185], v[26:29]
	s_waitcnt lgkmcnt(7)
	v_mfma_f32_16x16x32_bf16 v[86:89], v[238:241], v[178:181], v[86:89]
	v_mfma_f32_16x16x32_bf16 v[22:25], v[238:241], v[182:185], v[22:25]
	s_waitcnt lgkmcnt(6)
	v_mfma_f32_16x16x32_bf16 v[82:85], v[242:245], v[178:181], v[82:85]
	v_mfma_f32_16x16x32_bf16 v[18:21], v[242:245], v[182:185], v[18:21]
	s_waitcnt lgkmcnt(5)
	v_mfma_f32_16x16x32_bf16 v[78:81], v[206:209], v[178:181], v[78:81]
	v_mfma_f32_16x16x32_bf16 v[14:17], v[206:209], v[182:185], v[14:17]
	s_waitcnt lgkmcnt(4)
	v_mfma_f32_16x16x32_bf16 v[74:77], v[210:213], v[178:181], v[74:77]
	v_mfma_f32_16x16x32_bf16 v[10:13], v[210:213], v[182:185], v[10:13]
	s_waitcnt lgkmcnt(2)
	v_mfma_f32_16x16x32_bf16 v[70:73], v[214:217], v[178:181], v[70:73]
	v_mfma_f32_16x16x32_bf16 v[6:9], v[214:217], v[182:185], v[6:9]
	s_waitcnt lgkmcnt(0)
	v_mfma_f32_16x16x32_bf16 v[66:69], v[218:221], v[178:181], v[66:69]
	v_mfma_f32_16x16x32_bf16 v[2:5], v[218:221], v[182:185], v[2:5]
	ds_read2_b64 v[178:181], v172 offset0:8 offset1:12
	ds_read2_b64 v[182:185], v0 offset0:40 offset1:44
	ds_read2_b64 v[190:193], v222 offset0:72 offset1:76
	ds_read2_b64 v[194:197], v223 offset0:104 offset1:108
	ds_read2_b64 v[198:201], v224 offset0:136 offset1:140
	ds_read2_b64 v[202:205], v225 offset0:168 offset1:172
	ds_read_b64 v[206:207], v175 offset:13824
	ds_read_b64 v[208:209], v176 offset:32
	ds_read_b64 v[212:213], v177 offset:32
	ds_read_b64 v[210:211], v175 offset:16128
	s_waitcnt lgkmcnt(9)
	v_mfma_f32_16x16x32_bf16 v[94:97], v[178:181], v[130:133], v[94:97]
	v_mfma_f32_16x16x32_bf16 v[30:33], v[178:181], v[186:189], v[30:33]
	s_waitcnt lgkmcnt(8)
	v_mfma_f32_16x16x32_bf16 v[90:93], v[182:185], v[130:133], v[90:93]
	v_mfma_f32_16x16x32_bf16 v[26:29], v[182:185], v[186:189], v[26:29]
	s_waitcnt lgkmcnt(7)
	v_mfma_f32_16x16x32_bf16 v[86:89], v[190:193], v[130:133], v[86:89]
	v_mfma_f32_16x16x32_bf16 v[22:25], v[190:193], v[186:189], v[22:25]
	s_waitcnt lgkmcnt(6)
	v_mfma_f32_16x16x32_bf16 v[82:85], v[194:197], v[130:133], v[82:85]
	v_mfma_f32_16x16x32_bf16 v[18:21], v[194:197], v[186:189], v[18:21]
	s_waitcnt lgkmcnt(5)
	v_mfma_f32_16x16x32_bf16 v[78:81], v[198:201], v[130:133], v[78:81]
	v_mfma_f32_16x16x32_bf16 v[14:17], v[198:201], v[186:189], v[14:17]
	s_waitcnt lgkmcnt(4)
	v_mfma_f32_16x16x32_bf16 v[74:77], v[202:205], v[130:133], v[74:77]
	v_mfma_f32_16x16x32_bf16 v[10:13], v[202:205], v[186:189], v[10:13]
	s_waitcnt lgkmcnt(2)
	v_mfma_f32_16x16x32_bf16 v[70:73], v[206:209], v[130:133], v[70:73]
	v_mfma_f32_16x16x32_bf16 v[6:9], v[206:209], v[186:189], v[6:9]
	s_waitcnt lgkmcnt(0)
	v_mfma_f32_16x16x32_bf16 v[66:69], v[210:213], v[130:133], v[66:69]
	v_mfma_f32_16x16x32_bf16 v[2:5], v[210:213], v[186:189], v[2:5]
	s_branch .LBB0_645
